# P4 carry: only wave 0 of each WG polls the predecessor flags (merged masked queries, s_sleep 24), then a workgroup barrier; other waves wait at the barrier
# speedup vs baseline: 1.0642x; 1.0074x over previous
.LBB0_488:
	v_mov_b32_e32 v183, v165
	v_mov_b32_e32 v181, v165
	v_mov_b32_e32 v179, v165
	v_mov_b32_e32 v177, v165
	v_mov_b32_e32 v175, v165
	v_mov_b32_e32 v173, v165
	v_mov_b32_e32 v171, v165
	s_and_b32 s20, s63, 31
	v_lshlrev_b32_e32 v0, 1, v239
	s_and_b32 s53, s63, 0xffffffe0
	s_lshl_b32 s55, s62, 2
	v_cmp_gt_i32_e32 vcc, s20, v0
	v_mov_b32_e32 v30, 1.0
	v_mov_b32_e32 v31, 0
	v_mov_b32_e32 v29, 0
	v_mov_b32_e32 v27, 0
	v_mov_b32_e32 v25, 0
	v_mov_b32_e32 v23, 0
	v_mov_b32_e32 v21, 0
	v_mov_b32_e32 v19, 0
	v_mov_b32_e32 v17, 0
	v_mov_b32_e32 v28, 1.0
	v_mov_b32_e32 v26, 1.0
	v_mov_b32_e32 v24, 1.0
	v_mov_b32_e32 v22, 1.0
	v_mov_b32_e32 v20, 1.0
	v_mov_b32_e32 v18, 1.0
	v_mov_b32_e32 v16, 1.0
	s_and_saveexec_b64 s[8:9], vcc
	s_cbranch_execz .LBB0_534
	v_add_u32_e32 v2, s53, v0
	v_or_b32_e32 v204, 1, v0
	v_lshl_add_u32 v4, v2, 5, s55
	v_cmp_gt_i32_e64 s[60:61], s20, v204
	v_add_u32_e32 v204, 32, v4
	v_lshlrev_b32_e32 v208, 3, v238
	v_cndmask_b32_e64 v204, v4, v204, s[60:61]
	v_lshrrev_b32_e32 v206, 6, v226
	s_mov_b64 s[62:63], exec
	v_readfirstlane_b32 s21, v206
	s_cmp_lg_u32 s21, 0
	s_cbranch_scc1 .Lcarry_ready
	s_mov_b32 s21, 0x10000
.Lcarry_poll:
	global_load_dword v206, v4, s[34:35] sc1
	global_load_dword v210, v204, s[34:35] sc1
	s_waitcnt vmcnt(0)
	v_min_u32_e32 v206, v206, v210
	v_cmp_gt_u32_e32 vcc, 4, v206
	s_and_b64 exec, exec, vcc
	s_cbranch_execz .Lcarry_ready
	s_sleep 24
	s_add_i32 s21, s21, -1
	s_cmp_lg_u32 s21, 0
	s_cbranch_scc1 .Lcarry_poll
.Lcarry_ready:
	s_mov_b64 exec, s[62:63]
	s_barrier
	v_lshl_add_u32 v2, v2, 13, v208
	v_add_u32_e32 v4, 0x2000, v2
	global_load_dwordx2 v[30:31], v2, s[30:31] sc1
	global_load_dwordx2 v[28:29], v2, s[30:31] offset:8 sc1
	global_load_dwordx2 v[26:27], v2, s[30:31] offset:16 sc1
	global_load_dwordx2 v[24:25], v2, s[30:31] offset:24 sc1
	global_load_dwordx2 v[22:23], v2, s[30:31] offset:32 sc1
	global_load_dwordx2 v[20:21], v2, s[30:31] offset:40 sc1
	global_load_dwordx2 v[18:19], v2, s[30:31] offset:48 sc1
	global_load_dwordx2 v[16:17], v2, s[30:31] offset:56 sc1
	s_and_saveexec_b64 s[64:65], s[60:61]
	global_load_dwordx2 v[204:205], v4, s[30:31] sc1
	global_load_dwordx2 v[206:207], v4, s[30:31] offset:8 sc1
	global_load_dwordx2 v[208:209], v4, s[30:31] offset:16 sc1
	global_load_dwordx2 v[210:211], v4, s[30:31] offset:24 sc1
	global_load_dwordx2 v[212:213], v4, s[30:31] offset:32 sc1
	global_load_dwordx2 v[214:215], v4, s[30:31] offset:40 sc1
	global_load_dwordx2 v[216:217], v4, s[30:31] offset:48 sc1
	global_load_dwordx2 v[218:219], v4, s[30:31] offset:56 sc1
	s_mov_b64 exec, s[64:65]
	s_waitcnt vmcnt(0)
	v_fmac_f32_e32 v31, 0, v30
	v_fmac_f32_e32 v29, 0, v28
	v_fmac_f32_e32 v27, 0, v26
	v_fmac_f32_e32 v25, 0, v24
	v_fmac_f32_e32 v23, 0, v22
	v_fmac_f32_e32 v21, 0, v20
	v_fmac_f32_e32 v19, 0, v18
	v_fmac_f32_e32 v17, 0, v16
	s_and_saveexec_b64 s[64:65], s[60:61]
	v_fmac_f32_e32 v205, v31, v204
	v_fmac_f32_e32 v207, v29, v206
	v_mul_f32_e32 v30, v30, v204
	v_fmac_f32_e32 v209, v27, v208
	v_mul_f32_e32 v28, v28, v206
	v_fmac_f32_e32 v211, v25, v210
	v_mul_f32_e32 v26, v26, v208
	v_fmac_f32_e32 v213, v23, v212
	v_mul_f32_e32 v24, v24, v210
	v_fmac_f32_e32 v215, v21, v214
	v_mul_f32_e32 v22, v22, v212
	v_mul_f32_e32 v20, v20, v214
	v_fmac_f32_e32 v217, v19, v216
	v_fmac_f32_e32 v219, v17, v218
	v_mul_f32_e32 v18, v18, v216
	v_mul_f32_e32 v16, v16, v218
	v_mov_b32_e32 v31, v205
	v_mov_b32_e32 v29, v207
	v_mov_b32_e32 v27, v209
	v_mov_b32_e32 v25, v211
	v_mov_b32_e32 v23, v213
	v_mov_b32_e32 v21, v215
	v_mov_b32_e32 v19, v217
	v_mov_b32_e32 v17, v219
	s_mov_b64 exec, s[64:65]
